# MLA loop: the tile's LDS-DMA pieces issued between the QK MFMAs (unconditional) instead of back to back at the loop top
# speedup vs baseline: 1.0074x; 1.0074x over previous
; #define MFMA32(a, b, c) __builtin_amdgcn_mfma_f32_32x32x16_bf16((a), (b), (c), 0, 0, 0)
; DI int crow(int r, int hi) { return (r & 3) + 8 * (r >> 2) + 4 * hi; }
; #define VFRAG(dst, kk_) do { _Pragma("unroll") for (int mt = 0; mt < 4; ++mt) dst[mt] = *(const LAS bf16x8*)(vb + (32 * mt + r32) * VP + 16 * (kk_) + 8 * hf); } while (0)
; #define KFRAG(da, dc, ks_) do { da = *(const LAS bf16x8*)(kb + r32 * KP + 16 * (ks_) + 8 * hf); dc = *(const LAS bf16x8*)(kb + (32 + r32) * KP + 16 * (ks_) + 8 * hf); } while (0)
; DI void mla_attn_phase(LAS unsigned char* lds, const bf16_t* Qg, const bf16_t* Kg, const bf16_t* Vtg, bf16_t* MIX) {
;     ...
;                     bf16x8 ka0, kc0_, ka1, kc1_;
;                     KFRAG(ka0, kc0_, 0); KFRAG(ka1, kc1_, 1);
;                     __builtin_amdgcn_sched_barrier(0);
;                     f32x16 s0, s1;
; #pragma unroll
;                     for (int i = 0; i < 16; ++i) { s0[i] = 0.f; s1[i] = 0.f; }
;                     s0 = MFMA32(ka0, qf[0], s0); s1 = MFMA32(kc0_, qf[0], s1); KFRAG(ka0, kc0_, 2); __builtin_amdgcn_sched_barrier(0);
;                     s0 = MFMA32(ka1, qf[1], s0); s1 = MFMA32(kc1_, qf[1], s1); KFRAG(ka1, kc1_, 3); __builtin_amdgcn_sched_barrier(0);
;                     s0 = MFMA32(ka0, qf[2], s0); s1 = MFMA32(kc0_, qf[2], s1); KFRAG(ka0, kc0_, 4); __builtin_amdgcn_sched_barrier(0);
;                     s0 = MFMA32(ka1, qf[3], s0); s1 = MFMA32(kc1_, qf[3], s1); KFRAG(ka1, kc1_, 5); __builtin_amdgcn_sched_barrier(0);
;                     s0 = MFMA32(ka0, qf[4], s0); s1 = MFMA32(kc0_, qf[4], s1); s0 = MFMA32(ka1, qf[5], s0); s1 = MFMA32(kc1_, qf[5], s1);
;     ...
;                     bf16x8 vfa[4], vfb[4];
;                     VFRAG(vfa, 0); VFRAG(vfb, 1);
;                     __builtin_amdgcn_sched_barrier(0);
;                     if (kt >= 4 * qb) { const int qpos = q0 + r32;
; #pragma unroll
;                         for (int i = 0; i < 16; ++i) { const int key0 = 64 * kt + crow(i, hf); if (key0 > qpos) s0[i] = -INFINITY; if (key0 + 32 > qpos) s1[i] = -INFINITY; } }
.LBB0_361:
	s_cmp_gt_i32 s40, s39
	s_cbranch_scc1 .Lmla_skip1
	s_lshl_b32 s30, s41, 15
	s_add_i32 s30, s30, 0
	v_lshlrev_b32_e32 v0, 1, v166
	v_add_u32_e32 v1, s30, v0
	v_add_u32_e32 v3, v1, v230
	s_mov_b32 m0, s31
	ds_read_b128 v[4:7], v3
	ds_read_b128 v[8:11], v3 offset:32
	ds_read_b128 v[12:15], v3 offset:6656
	ds_read_b128 v[136:139], v3 offset:6688
	s_waitcnt lgkmcnt(0)
	v_mfma_f32_32x32x16_bf16 v[80:95], v[4:7], v[112:115], 0
	global_load_lds_dwordx4 v[210:211], off
	ds_read_b128 v[4:7], v3 offset:64
	ds_read_b128 v[140:143], v3 offset:6720
	v_mfma_f32_32x32x16_bf16 v[80:95], v[8:11], v[116:119], v[80:95]
	s_add_i32 m0, s31, 0x2000
	ds_read_b128 v[8:11], v3 offset:96
	ds_read_b128 v[144:147], v3 offset:6752
	s_waitcnt lgkmcnt(0)
	v_mfma_f32_32x32x16_bf16 v[80:95], v[4:7], v[120:123], v[80:95]
	ds_read_b128 v[4:7], v3 offset:128
	ds_read_b128 v[148:151], v3 offset:6784
	v_mfma_f32_32x32x16_bf16 v[80:95], v[8:11], v[124:127], v[80:95]
	global_load_lds_dwordx4 v[212:213], off
	ds_read_b128 v[8:11], v3 offset:160
	ds_read_b128 v[236:239], v3 offset:6816
	v_mfma_f32_32x32x16_bf16 v[96:111], v[12:15], v[112:115], 0
	s_add_i32 m0, s31, 0x4000
	v_add_u32_e32 v1, v1, v232
	v_mfma_f32_32x32x16_bf16 v[96:111], v[136:139], v[116:119], v[96:111]
	v_mfma_f32_32x32x16_bf16 v[96:111], v[140:143], v[120:123], v[96:111]
	global_load_lds_dwordx4 v[214:215], off
	v_mfma_f32_32x32x16_bf16 v[96:111], v[144:147], v[124:127], v[96:111]
	s_add_i32 m0, s31, 0x6000
	ds_read_b128 v[144:147], v1 offset:13312
	ds_read_b128 v[140:143], v1 offset:17920
	s_waitcnt lgkmcnt(2)
	v_mfma_f32_32x32x16_bf16 v[80:95], v[4:7], v[128:131], v[80:95]
	v_mfma_f32_32x32x16_bf16 v[96:111], v[148:151], v[128:131], v[96:111]
	global_load_lds_dwordx4 v[216:217], off
	ds_read_b128 v[148:151], v1 offset:22528
	ds_read_b128 v[152:155], v1 offset:27136
	v_add3_u32 v1, s30, v232, v0
	v_mfma_f32_32x32x16_bf16 v[80:95], v[8:11], v[132:135], v[80:95]
	ds_read_b128 v[136:139], v1 offset:13344
	ds_read_b128 v[12:15], v1 offset:17952
	ds_read_b128 v[4:7], v1 offset:22560
	ds_read_b128 v[8:11], v1 offset:27168
	v_mfma_f32_32x32x16_bf16 v[96:111], v[236:239], v[132:135], v[96:111]
	s_cmp_lt_i32 s42, s8
	s_cbranch_scc1 .LBB0_364
	v_add_u32_e32 v0, s40, v231
	v_add_u32_e32 v3, 32, v0
	v_cmp_le_i32_e32 vcc, v3, v167
	v_add_u32_e32 v3, 33, v0
	s_nop 5
	v_cndmask_b32_e32 v96, v229, v96, vcc
	v_cmp_lt_i32_e32 vcc, v0, v167
	s_nop 1
	v_cndmask_b32_e32 v81, v229, v81, vcc
	v_cmp_le_i32_e32 vcc, v0, v167
	s_nop 1
	v_cndmask_b32_e32 v80, v229, v80, vcc
	v_cmp_le_i32_e32 vcc, v3, v167
	v_add_u32_e32 v3, 2, v0
	s_nop 0
	v_cndmask_b32_e32 v97, v229, v97, vcc
	v_cmp_le_i32_e32 vcc, v3, v167
	v_add_u32_e32 v3, 34, v0
	s_nop 0
	v_cndmask_b32_e32 v82, v229, v82, vcc
	v_cmp_le_i32_e32 vcc, v3, v167
	v_add_u32_e32 v3, 3, v0
	s_nop 0
	v_cndmask_b32_e32 v98, v229, v98, vcc
	v_cmp_le_i32_e32 vcc, v3, v167
	v_add_u32_e32 v3, 35, v0
	s_nop 0
	v_cndmask_b32_e32 v83, v229, v83, vcc
	v_cmp_le_i32_e32 vcc, v3, v167
	v_add_u32_e32 v3, 8, v0
	s_nop 0
	v_cndmask_b32_e32 v99, v229, v99, vcc
	v_cmp_le_i32_e32 vcc, v3, v167
	v_add_u32_e32 v3, 40, v0
	s_nop 0
	v_cndmask_b32_e32 v84, v229, v84, vcc
	v_cmp_le_i32_e32 vcc, v3, v167
	v_add_u32_e32 v3, 9, v0
	s_nop 0
	v_cndmask_b32_e32 v100, v229, v100, vcc
	v_cmp_le_i32_e32 vcc, v3, v167
	v_add_u32_e32 v3, 41, v0
	s_nop 0
	v_cndmask_b32_e32 v85, v229, v85, vcc
	v_cmp_le_i32_e32 vcc, v3, v167
	v_add_u32_e32 v3, 10, v0
	s_nop 0
	v_cndmask_b32_e32 v101, v229, v101, vcc
	v_cmp_le_i32_e32 vcc, v3, v167
	v_add_u32_e32 v3, 42, v0
	s_nop 0
	v_cndmask_b32_e32 v86, v229, v86, vcc
	v_cmp_le_i32_e32 vcc, v3, v167
	v_add_u32_e32 v3, 11, v0
	s_nop 0
	v_cndmask_b32_e32 v102, v229, v102, vcc
	v_cmp_le_i32_e32 vcc, v3, v167
	v_add_u32_e32 v3, 43, v0
	s_nop 0
	v_cndmask_b32_e32 v87, v229, v87, vcc
	v_cmp_le_i32_e32 vcc, v3, v167
	v_add_u32_e32 v3, 16, v0
	s_nop 0
	v_cndmask_b32_e32 v103, v229, v103, vcc
	v_cmp_le_i32_e32 vcc, v3, v167
	v_add_u32_e32 v3, 48, v0
	s_nop 0
	v_cndmask_b32_e32 v88, v229, v88, vcc
	v_cmp_le_i32_e32 vcc, v3, v167
	v_add_u32_e32 v3, 17, v0
	s_nop 0
	v_cndmask_b32_e32 v104, v229, v104, vcc
	v_cmp_le_i32_e32 vcc, v3, v167
	v_add_u32_e32 v3, 49, v0
	s_nop 0
	v_cndmask_b32_e32 v89, v229, v89, vcc
	v_cmp_le_i32_e32 vcc, v3, v167
	v_add_u32_e32 v3, 18, v0
	s_nop 0
	v_cndmask_b32_e32 v105, v229, v105, vcc
	v_cmp_le_i32_e32 vcc, v3, v167
	v_add_u32_e32 v3, 50, v0
	s_nop 0
	v_cndmask_b32_e32 v90, v229, v90, vcc
	v_cmp_le_i32_e32 vcc, v3, v167
	v_add_u32_e32 v3, 19, v0
	s_nop 0
	v_cndmask_b32_e32 v106, v229, v106, vcc
	v_cmp_le_i32_e32 vcc, v3, v167
	v_add_u32_e32 v3, 51, v0
	s_nop 0
	v_cndmask_b32_e32 v91, v229, v91, vcc
	v_cmp_le_i32_e32 vcc, v3, v167
	v_add_u32_e32 v3, 24, v0
	s_nop 0
	v_cndmask_b32_e32 v107, v229, v107, vcc
	v_cmp_le_i32_e32 vcc, v3, v167
	v_add_u32_e32 v3, 56, v0
	s_nop 0
	v_cndmask_b32_e32 v92, v229, v92, vcc
	v_cmp_le_i32_e32 vcc, v3, v167
	v_add_u32_e32 v3, 25, v0
	s_nop 0
	v_cndmask_b32_e32 v108, v229, v108, vcc
	v_cmp_le_i32_e32 vcc, v3, v167
	v_add_u32_e32 v3, 57, v0
	s_nop 0
	v_cndmask_b32_e32 v93, v229, v93, vcc
	v_cmp_le_i32_e32 vcc, v3, v167
	v_add_u32_e32 v3, 26, v0
	s_nop 0
	v_cndmask_b32_e32 v109, v229, v109, vcc
	v_cmp_le_i32_e32 vcc, v3, v167
	v_add_u32_e32 v3, 58, v0
	s_nop 0
	v_cndmask_b32_e32 v94, v229, v94, vcc
	v_cmp_le_i32_e32 vcc, v3, v167
	v_add_u32_e32 v3, 27, v0
	v_add_u32_e32 v0, 59, v0
	v_cndmask_b32_e32 v110, v229, v110, vcc
	v_cmp_le_i32_e32 vcc, v3, v167
	s_nop 1
	v_cndmask_b32_e32 v95, v229, v95, vcc
	v_cmp_le_i32_e32 vcc, v0, v167
	s_nop 1
	v_cndmask_b32_e32 v111, v229, v111, vcc
